# norm phases: wave sum with 2 SGPR temps, literal consts; otherwise as v33 (W6 scan + pipelined adaLN norm P5/P12)
# speedup vs baseline: 1.0084x; 1.0029x over previous
; __device__ __forceinline__ int opaque_tid() { int t = threadIdx.x; asm volatile("" : "+v"(t)); return t; }
; __device__ __forceinline__ unsigned cvt_pk_bf16(float lo, float hi) { unsigned r; asm volatile("v_cvt_pk_bf16_f32 %0, %1, %2" : "=v"(r) : "v"(lo), "v"(hi)); return r; }
; __device__ __forceinline__ void phase_norm_mod(const float* x, const float* mod_shift, const float* mod_scale, bf16_t* H, int) {
;     const int tid = opaque_tid(), lane = tid & 63, wave = tid >> 6;
;     const int gw = blockIdx.x * NWAVES + wave, NGW = gridDim.x * NWAVES;
;     constexpr int NR = 4;
;     for (int m0 = gw; m0 < M; m0 += NR * NGW) {
;         f32x4 v[NR][4];
; #pragma unroll
;         for (int r = 0; r < NR; ++r) { const int m = M - 1 - (m0 + r * NGW < M ? m0 + r * NGW : m0); const f32x4* xr = (const f32x4*)(x + (size_t)m * D) + lane;
; #pragma unroll
;             for (int j = 0; j < 4; ++j) v[r][j] = xr[64 * j]; }
; #pragma unroll
;         for (int r = 0; r < NR; ++r) { const int m = M - 1 - (m0 + r * NGW); if (m >= 0) {
;             const int b = m >> 12; float s = 0.f;
; #pragma unroll
;             for (int j = 0; j < 4; ++j) s += (v[r][j].x * v[r][j].x + v[r][j].y * v[r][j].y) + (v[r][j].z * v[r][j].z + v[r][j].w * v[r][j].w);
;             const float rstd = 1.0f / sqrtf(wave_sum(s) * (1.f / D) + 1e-6f);
;             const f32x4* sh = (const f32x4*)(mod_shift + (size_t)b * 6144) + lane;
;             const f32x4* sc = (const f32x4*)(mod_scale + (size_t)b * 6144) + lane;
;             u32x2* o = (u32x2*)(H + (size_t)m * D) + lane;
; #pragma unroll
;             for (int j = 0; j < 4; ++j) { const f32x4 a = sh[64 * j], c = sc[64 * j]; const f32x4 h = v[r][j] * rstd * (c + 1.0f) + a;
;                 u32x2 w; w.x = cvt_pk_bf16(h.x, h.y); w.y = cvt_pk_bf16(h.z, h.w); o[64 * j] = w; } } }
; template <int l> __device__ __forceinline__ void layer(const Args& a, LAS unsigned char* lds, cg::grid_group& grid, const XcdBarrier& xbar, int& ph, const int lo, const int hi) {
;     ...
;     if (RUN) phase_norm_mod(a.out, mod + 3 * 1024, mod + 4 * 1024, H, 0);
.LBB0_1052:
	s_cmp_lt_i32 s90, 6
	s_cselect_b64 s[8:9], -1, 0
	s_and_b64 s[0:1], s[8:9], s[0:1]
	s_andn2_b64 vcc, exec, s[0:1]
	s_cbranch_vccnz .LBB0_1063
	s_mov_b64 s[10:11], exec
	v_mov_b32_e32 v178, 0xf800000
	v_lshrrev_b32_e32 v176, 6, v180
	v_and_b32_e32 v177, 63, v180
	v_readfirstlane_b32 s0, v176
	v_lshlrev_b32_e32 v176, 4, v177
	v_lshlrev_b32_e32 v177, 3, v177
	v_mov_b32_e32 v170, 0x358637bd
	v_mov_b32_e32 v171, 0x260
	s_lshl_b32 s1, s24, 3
	s_add_i32 s0, s0, s1
	s_lshl_b32 s2, s28, 3
	s_mul_i32 s1, s2, 3
	s_mov_b32 s18, s0
	s_add_i32 s19, s0, s2
	s_add_i32 s20, s19, s2
	s_cmp_lt_u32 s0, 0x10000
	s_cbranch_scc0 .LNa_done
	s_cmp_lt_u32 s18, 0x10000
	s_cselect_b32 s3, s18, s0
	s_sub_u32 s3, 0xffff, s3
	s_lshl_b32 s4, s3, 12
	s_add_u32 s6, s86, s4
	s_addc_u32 s7, s87, 0
	s_lshr_b32 s4, s3, 12
	s_mul_i32 s4, s4, 0x6000
	s_add_u32 s12, s88, s4
	s_addc_u32 s13, s89, 0
	s_add_u32 s14, s12, 0x104000
	s_addc_u32 s15, s13, 0
	s_add_u32 s12, s12, 0x103000
	s_addc_u32 s13, s13, 0
	global_load_dwordx4 v[0:3], v176, s[6:7]
	global_load_dwordx4 v[4:7], v176, s[6:7] offset:1024
	global_load_dwordx4 v[8:11], v176, s[6:7] offset:2048
	global_load_dwordx4 v[12:15], v176, s[6:7] offset:3072
	global_load_dwordx4 v[16:19], v176, s[14:15]
	global_load_dwordx4 v[20:23], v176, s[14:15] offset:1024
	global_load_dwordx4 v[24:27], v176, s[14:15] offset:2048
	global_load_dwordx4 v[28:31], v176, s[14:15] offset:3072
	global_load_dwordx4 v[32:35], v176, s[12:13]
	global_load_dwordx4 v[36:39], v176, s[12:13] offset:1024
	global_load_dwordx4 v[40:43], v176, s[12:13] offset:2048
	global_load_dwordx4 v[44:47], v176, s[12:13] offset:3072
	s_cmp_lt_u32 s19, 0x10000
	s_cselect_b32 s3, s19, s0
	s_sub_u32 s3, 0xffff, s3
	s_lshl_b32 s4, s3, 12
	s_add_u32 s6, s86, s4
	s_addc_u32 s7, s87, 0
	s_lshr_b32 s4, s3, 12
	s_mul_i32 s4, s4, 0x6000
	s_add_u32 s12, s88, s4
	s_addc_u32 s13, s89, 0
	s_add_u32 s14, s12, 0x104000
	s_addc_u32 s15, s13, 0
	s_add_u32 s12, s12, 0x103000
	s_addc_u32 s13, s13, 0
	global_load_dwordx4 v[48:51], v176, s[6:7]
	global_load_dwordx4 v[52:55], v176, s[6:7] offset:1024
	global_load_dwordx4 v[56:59], v176, s[6:7] offset:2048
	global_load_dwordx4 v[60:63], v176, s[6:7] offset:3072
	global_load_dwordx4 v[64:67], v176, s[14:15]
	global_load_dwordx4 v[68:71], v176, s[14:15] offset:1024
	global_load_dwordx4 v[72:75], v176, s[14:15] offset:2048
	global_load_dwordx4 v[76:79], v176, s[14:15] offset:3072
	global_load_dwordx4 v[80:83], v176, s[12:13]
	global_load_dwordx4 v[84:87], v176, s[12:13] offset:1024
	global_load_dwordx4 v[88:91], v176, s[12:13] offset:2048
	global_load_dwordx4 v[92:95], v176, s[12:13] offset:3072
	s_cmp_lt_u32 s20, 0x10000
	s_cselect_b32 s3, s20, s0
	s_sub_u32 s3, 0xffff, s3
	s_lshl_b32 s4, s3, 12
	s_add_u32 s6, s86, s4
	s_addc_u32 s7, s87, 0
	s_lshr_b32 s4, s3, 12
	s_mul_i32 s4, s4, 0x6000
	s_add_u32 s12, s88, s4
	s_addc_u32 s13, s89, 0
	s_add_u32 s14, s12, 0x104000
	s_addc_u32 s15, s13, 0
	s_add_u32 s12, s12, 0x103000
	s_addc_u32 s13, s13, 0
	global_load_dwordx4 v[96:99], v176, s[6:7]
	global_load_dwordx4 v[100:103], v176, s[6:7] offset:1024
	global_load_dwordx4 v[104:107], v176, s[6:7] offset:2048
	global_load_dwordx4 v[108:111], v176, s[6:7] offset:3072
	global_load_dwordx4 v[112:115], v176, s[14:15]
	global_load_dwordx4 v[116:119], v176, s[14:15] offset:1024
	global_load_dwordx4 v[120:123], v176, s[14:15] offset:2048
	global_load_dwordx4 v[124:127], v176, s[14:15] offset:3072
	global_load_dwordx4 v[128:131], v176, s[12:13]
	global_load_dwordx4 v[132:135], v176, s[12:13] offset:1024
	global_load_dwordx4 v[136:139], v176, s[12:13] offset:2048
	global_load_dwordx4 v[140:143], v176, s[12:13] offset:3072
.LNa_loop:
	s_cmp_lt_u32 s18, 0x10000
	s_cbranch_scc0 .LNa_done
	s_waitcnt vmcnt(24)
	v_pk_mul_f32 v[172:173], v[0:1], v[0:1]
	v_pk_mul_f32 v[174:175], v[2:3], v[2:3]
	v_pk_fma_f32 v[172:173], v[4:5], v[4:5], v[172:173]
	v_pk_fma_f32 v[174:175], v[6:7], v[6:7], v[174:175]
	v_pk_fma_f32 v[172:173], v[8:9], v[8:9], v[172:173]
	v_pk_fma_f32 v[174:175], v[10:11], v[10:11], v[174:175]
	v_pk_fma_f32 v[172:173], v[12:13], v[12:13], v[172:173]
	v_pk_fma_f32 v[174:175], v[14:15], v[14:15], v[174:175]
	v_pk_add_f32 v[172:173], v[172:173], v[174:175]
	s_sub_u32 s3, 0xffff, s18
	s_lshl_b32 s4, s3, 11
	v_add_f32_e32 v160, v172, v173
	s_add_u32 s16, s88, s4
	s_addc_u32 s17, s89, 0
	s_nop 1
	v_add_f32_dpp v160, v160, v160 quad_perm:[1,0,3,2] row_mask:0xf bank_mask:0xf bound_ctrl:1
	s_nop 1
	v_add_f32_dpp v160, v160, v160 quad_perm:[2,3,0,1] row_mask:0xf bank_mask:0xf bound_ctrl:1
	s_nop 1
	v_add_f32_dpp v160, v160, v160 row_half_mirror row_mask:0xf bank_mask:0xf bound_ctrl:1
	s_nop 1
	v_add_f32_dpp v160, v160, v160 row_mirror row_mask:0xf bank_mask:0xf bound_ctrl:1
	s_add_u32 s16, s16, 0x3c00000
	s_addc_u32 s17, s17, 0
	v_readlane_b32 s4, v160, 0
	v_readlane_b32 s5, v160, 16
	v_readlane_b32 s3, v160, 32
	s_nop 1
	v_mov_b32_e32 v161, s4
	v_add_f32_e32 v161, s5, v161
	v_readlane_b32 s4, v160, 48
	v_add_f32_e32 v161, s3, v161
	s_nop 1
	v_add_f32_e32 v160, s4, v161
	v_fmamk_f32 v160, v160, 0x3a800000, v170
	v_mul_f32_e32 v161, 0x4f800000, v160
	v_cmp_gt_f32_e32 vcc, v178, v160
	s_nop 1
	v_cndmask_b32_e32 v162, v160, v161, vcc
	v_sqrt_f32_e32 v164, v162
	s_nop 0
	v_add_u32_e32 v165, -1, v164
	v_add_u32_e32 v166, 1, v164
	v_fma_f32 v167, -v165, v164, v162
	v_fma_f32 v168, -v166, v164, v162
	v_cmp_ge_f32_e64 s[4:5], 0, v167
	s_nop 1
	v_cndmask_b32_e64 v164, v164, v165, s[4:5]
	v_cmp_lt_f32_e64 s[4:5], 0, v168
	s_nop 1
	v_cndmask_b32_e64 v164, v164, v166, s[4:5]
	v_mul_f32_e32 v165, 0x37800000, v164
	v_cndmask_b32_e32 v164, v164, v165, vcc
; __device__ __forceinline__ unsigned cvt_pk_bf16(float lo, float hi) { unsigned r; asm volatile("v_cvt_pk_bf16_f32 %0, %1, %2" : "=v"(r) : "v"(lo), "v"(hi)); return r; }
; __device__ __forceinline__ void phase_norm_mod(const float* x, const float* mod_shift, const float* mod_scale, bf16_t* H, int) {
;     ...
;         for (int r = 0; r < NR; ++r) { const int m = M - 1 - (m0 + r * NGW < M ? m0 + r * NGW : m0); const f32x4* xr = (const f32x4*)(x + (size_t)m * D) + lane;
; #pragma unroll
;             for (int j = 0; j < 4; ++j) v[r][j] = xr[64 * j]; }
; #pragma unroll
;         for (int r = 0; r < NR; ++r) { const int m = M - 1 - (m0 + r * NGW); if (m >= 0) {
;             const int b = m >> 12; float s = 0.f;
; #pragma unroll
;             for (int j = 0; j < 4; ++j) s += (v[r][j].x * v[r][j].x + v[r][j].y * v[r][j].y) + (v[r][j].z * v[r][j].z + v[r][j].w * v[r][j].w);
;             const float rstd = 1.0f / sqrtf(wave_sum(s) * (1.f / D) + 1e-6f);
;             const f32x4* sh = (const f32x4*)(mod_shift + (size_t)b * 6144) + lane;
;             const f32x4* sc = (const f32x4*)(mod_scale + (size_t)b * 6144) + lane;
;             u32x2* o = (u32x2*)(H + (size_t)m * D) + lane;
; #pragma unroll
;             for (int j = 0; j < 4; ++j) { const f32x4 a = sh[64 * j], c = sc[64 * j]; const f32x4 h = v[r][j] * rstd * (c + 1.0f) + a;
;                 u32x2 w; w.x = cvt_pk_bf16(h.x, h.y); w.y = cvt_pk_bf16(h.z, h.w); o[64 * j] = w; } } }
	v_cmp_class_f32_e32 vcc, v162, v171
	s_nop 1
	v_cndmask_b32_e32 v162, v164, v162, vcc
	v_div_scale_f32 v164, s[4:5], v162, v162, 1.0
	v_rcp_f32_e32 v165, v164
	v_div_scale_f32 v166, vcc, 1.0, v162, 1.0
	v_fma_f32 v167, -v164, v165, 1.0
	v_fmac_f32_e32 v165, v167, v165
	v_mul_f32_e32 v167, v166, v165
	v_fma_f32 v168, -v164, v167, v166
	v_fmac_f32_e32 v167, v168, v165
	v_fma_f32 v164, -v164, v167, v166
	v_div_fmas_f32 v164, v164, v165, v167
	v_div_fixup_f32 v162, v164, v162, 1.0
	v_pk_mul_f32 v[0:1], v[0:1], v[162:163] op_sel_hi:[1,0]
	v_pk_mul_f32 v[2:3], v[2:3], v[162:163] op_sel_hi:[1,0]
	v_pk_add_f32 v[16:17], v[16:17], 1.0 op_sel_hi:[1,0]
	v_pk_add_f32 v[18:19], v[18:19], 1.0 op_sel_hi:[1,0]
	v_pk_fma_f32 v[0:1], v[16:17], v[0:1], v[32:33]
	v_pk_fma_f32 v[2:3], v[18:19], v[2:3], v[34:35]
	v_cvt_pk_bf16_f32 v152, v0, v1
	v_cvt_pk_bf16_f32 v153, v2, v3
	v_pk_mul_f32 v[4:5], v[4:5], v[162:163] op_sel_hi:[1,0]
	v_pk_mul_f32 v[6:7], v[6:7], v[162:163] op_sel_hi:[1,0]
	v_pk_add_f32 v[20:21], v[20:21], 1.0 op_sel_hi:[1,0]
	v_pk_add_f32 v[22:23], v[22:23], 1.0 op_sel_hi:[1,0]
	v_pk_fma_f32 v[4:5], v[20:21], v[4:5], v[36:37]
	v_pk_fma_f32 v[6:7], v[22:23], v[6:7], v[38:39]
	v_cvt_pk_bf16_f32 v154, v4, v5
	v_cvt_pk_bf16_f32 v155, v6, v7
	v_pk_mul_f32 v[8:9], v[8:9], v[162:163] op_sel_hi:[1,0]
	v_pk_mul_f32 v[10:11], v[10:11], v[162:163] op_sel_hi:[1,0]
	v_pk_add_f32 v[24:25], v[24:25], 1.0 op_sel_hi:[1,0]
	v_pk_add_f32 v[26:27], v[26:27], 1.0 op_sel_hi:[1,0]
	v_pk_fma_f32 v[8:9], v[24:25], v[8:9], v[40:41]
	v_pk_fma_f32 v[10:11], v[26:27], v[10:11], v[42:43]
	v_cvt_pk_bf16_f32 v156, v8, v9
	v_cvt_pk_bf16_f32 v157, v10, v11
	v_pk_mul_f32 v[12:13], v[12:13], v[162:163] op_sel_hi:[1,0]
	v_pk_mul_f32 v[14:15], v[14:15], v[162:163] op_sel_hi:[1,0]
	v_pk_add_f32 v[28:29], v[28:29], 1.0 op_sel_hi:[1,0]
	v_pk_add_f32 v[30:31], v[30:31], 1.0 op_sel_hi:[1,0]
	v_pk_fma_f32 v[12:13], v[28:29], v[12:13], v[44:45]
	v_pk_fma_f32 v[14:15], v[30:31], v[14:15], v[46:47]
	v_cvt_pk_bf16_f32 v158, v12, v13
	v_cvt_pk_bf16_f32 v159, v14, v15
	global_store_dwordx2 v177, v[152:153], s[16:17]
	global_store_dwordx2 v177, v[154:155], s[16:17] offset:512
	global_store_dwordx2 v177, v[156:157], s[16:17] offset:1024
	global_store_dwordx2 v177, v[158:159], s[16:17] offset:1536
	s_add_i32 s18, s18, s1
	s_cmp_lt_u32 s18, 0x10000
	s_cselect_b32 s3, s18, s0
	s_sub_u32 s3, 0xffff, s3
	s_lshl_b32 s4, s3, 12
	s_add_u32 s6, s86, s4
	s_addc_u32 s7, s87, 0
	s_lshr_b32 s4, s3, 12
	s_mul_i32 s4, s4, 0x6000
	s_add_u32 s12, s88, s4
	s_addc_u32 s13, s89, 0
	s_add_u32 s14, s12, 0x104000
	s_addc_u32 s15, s13, 0
	s_add_u32 s12, s12, 0x103000
	s_addc_u32 s13, s13, 0
	global_load_dwordx4 v[0:3], v176, s[6:7]
	global_load_dwordx4 v[4:7], v176, s[6:7] offset:1024
	global_load_dwordx4 v[8:11], v176, s[6:7] offset:2048
	global_load_dwordx4 v[12:15], v176, s[6:7] offset:3072
	global_load_dwordx4 v[16:19], v176, s[14:15]
	global_load_dwordx4 v[20:23], v176, s[14:15] offset:1024
	global_load_dwordx4 v[24:27], v176, s[14:15] offset:2048
	global_load_dwordx4 v[28:31], v176, s[14:15] offset:3072
	global_load_dwordx4 v[32:35], v176, s[12:13]
	global_load_dwordx4 v[36:39], v176, s[12:13] offset:1024
	global_load_dwordx4 v[40:43], v176, s[12:13] offset:2048
	global_load_dwordx4 v[44:47], v176, s[12:13] offset:3072
	s_cmp_lt_u32 s19, 0x10000
	s_cbranch_scc0 .LNa_done
	s_waitcnt vmcnt(24)
	v_pk_mul_f32 v[172:173], v[48:49], v[48:49]
	v_pk_mul_f32 v[174:175], v[50:51], v[50:51]
	v_pk_fma_f32 v[172:173], v[52:53], v[52:53], v[172:173]
	v_pk_fma_f32 v[174:175], v[54:55], v[54:55], v[174:175]
	v_pk_fma_f32 v[172:173], v[56:57], v[56:57], v[172:173]
	v_pk_fma_f32 v[174:175], v[58:59], v[58:59], v[174:175]
	v_pk_fma_f32 v[172:173], v[60:61], v[60:61], v[172:173]
	v_pk_fma_f32 v[174:175], v[62:63], v[62:63], v[174:175]
	v_pk_add_f32 v[172:173], v[172:173], v[174:175]
	s_sub_u32 s3, 0xffff, s19
	s_lshl_b32 s4, s3, 11
	v_add_f32_e32 v160, v172, v173
	s_add_u32 s16, s88, s4
	s_addc_u32 s17, s89, 0
	s_nop 1
	v_add_f32_dpp v160, v160, v160 quad_perm:[1,0,3,2] row_mask:0xf bank_mask:0xf bound_ctrl:1
	s_nop 1
	v_add_f32_dpp v160, v160, v160 quad_perm:[2,3,0,1] row_mask:0xf bank_mask:0xf bound_ctrl:1
	s_nop 1
	v_add_f32_dpp v160, v160, v160 row_half_mirror row_mask:0xf bank_mask:0xf bound_ctrl:1
	s_nop 1
	v_add_f32_dpp v160, v160, v160 row_mirror row_mask:0xf bank_mask:0xf bound_ctrl:1
	s_add_u32 s16, s16, 0x3c00000
	s_addc_u32 s17, s17, 0
	v_readlane_b32 s4, v160, 0
	v_readlane_b32 s5, v160, 16
	v_readlane_b32 s3, v160, 32
	s_nop 1
	v_mov_b32_e32 v161, s4
	v_add_f32_e32 v161, s5, v161
	v_readlane_b32 s4, v160, 48
	v_add_f32_e32 v161, s3, v161
	s_nop 1
	v_add_f32_e32 v160, s4, v161
	v_fmamk_f32 v160, v160, 0x3a800000, v170
	v_mul_f32_e32 v161, 0x4f800000, v160
	v_cmp_gt_f32_e32 vcc, v178, v160
	s_nop 1
	v_cndmask_b32_e32 v162, v160, v161, vcc
	v_sqrt_f32_e32 v164, v162
	s_nop 0
	v_add_u32_e32 v165, -1, v164
	v_add_u32_e32 v166, 1, v164
	v_fma_f32 v167, -v165, v164, v162
	v_fma_f32 v168, -v166, v164, v162
	v_cmp_ge_f32_e64 s[4:5], 0, v167
	s_nop 1
	v_cndmask_b32_e64 v164, v164, v165, s[4:5]
	v_cmp_lt_f32_e64 s[4:5], 0, v168
	s_nop 1
	v_cndmask_b32_e64 v164, v164, v166, s[4:5]
	v_mul_f32_e32 v165, 0x37800000, v164
	v_cndmask_b32_e32 v164, v164, v165, vcc
	v_cmp_class_f32_e32 vcc, v162, v171
	s_nop 1
	v_cndmask_b32_e32 v162, v164, v162, vcc
	v_div_scale_f32 v164, s[4:5], v162, v162, 1.0
	v_rcp_f32_e32 v165, v164
	v_div_scale_f32 v166, vcc, 1.0, v162, 1.0
	v_fma_f32 v167, -v164, v165, 1.0
	v_fmac_f32_e32 v165, v167, v165
	v_mul_f32_e32 v167, v166, v165
	v_fma_f32 v168, -v164, v167, v166
	v_fmac_f32_e32 v167, v168, v165
; __device__ __forceinline__ unsigned cvt_pk_bf16(float lo, float hi) { unsigned r; asm volatile("v_cvt_pk_bf16_f32 %0, %1, %2" : "=v"(r) : "v"(lo), "v"(hi)); return r; }
; __device__ __forceinline__ void phase_norm_mod(const float* x, const float* mod_shift, const float* mod_scale, bf16_t* H, int) {
;     ...
;         for (int r = 0; r < NR; ++r) { const int m = M - 1 - (m0 + r * NGW < M ? m0 + r * NGW : m0); const f32x4* xr = (const f32x4*)(x + (size_t)m * D) + lane;
; #pragma unroll
;             for (int j = 0; j < 4; ++j) v[r][j] = xr[64 * j]; }
; #pragma unroll
;         for (int r = 0; r < NR; ++r) { const int m = M - 1 - (m0 + r * NGW); if (m >= 0) {
;             const int b = m >> 12; float s = 0.f;
; #pragma unroll
;             for (int j = 0; j < 4; ++j) s += (v[r][j].x * v[r][j].x + v[r][j].y * v[r][j].y) + (v[r][j].z * v[r][j].z + v[r][j].w * v[r][j].w);
;             const float rstd = 1.0f / sqrtf(wave_sum(s) * (1.f / D) + 1e-6f);
;             const f32x4* sh = (const f32x4*)(mod_shift + (size_t)b * 6144) + lane;
;             const f32x4* sc = (const f32x4*)(mod_scale + (size_t)b * 6144) + lane;
;             u32x2* o = (u32x2*)(H + (size_t)m * D) + lane;
; #pragma unroll
;             for (int j = 0; j < 4; ++j) { const f32x4 a = sh[64 * j], c = sc[64 * j]; const f32x4 h = v[r][j] * rstd * (c + 1.0f) + a;
;                 u32x2 w; w.x = cvt_pk_bf16(h.x, h.y); w.y = cvt_pk_bf16(h.z, h.w); o[64 * j] = w; } } }
	v_fma_f32 v164, -v164, v167, v166
	v_div_fmas_f32 v164, v164, v165, v167
	v_div_fixup_f32 v162, v164, v162, 1.0
	v_pk_mul_f32 v[48:49], v[48:49], v[162:163] op_sel_hi:[1,0]
	v_pk_mul_f32 v[50:51], v[50:51], v[162:163] op_sel_hi:[1,0]
	v_pk_add_f32 v[64:65], v[64:65], 1.0 op_sel_hi:[1,0]
	v_pk_add_f32 v[66:67], v[66:67], 1.0 op_sel_hi:[1,0]
	v_pk_fma_f32 v[48:49], v[64:65], v[48:49], v[80:81]
	v_pk_fma_f32 v[50:51], v[66:67], v[50:51], v[82:83]
	v_cvt_pk_bf16_f32 v152, v48, v49
	v_cvt_pk_bf16_f32 v153, v50, v51
	v_pk_mul_f32 v[52:53], v[52:53], v[162:163] op_sel_hi:[1,0]
	v_pk_mul_f32 v[54:55], v[54:55], v[162:163] op_sel_hi:[1,0]
	v_pk_add_f32 v[68:69], v[68:69], 1.0 op_sel_hi:[1,0]
	v_pk_add_f32 v[70:71], v[70:71], 1.0 op_sel_hi:[1,0]
	v_pk_fma_f32 v[52:53], v[68:69], v[52:53], v[84:85]
	v_pk_fma_f32 v[54:55], v[70:71], v[54:55], v[86:87]
	v_cvt_pk_bf16_f32 v154, v52, v53
	v_cvt_pk_bf16_f32 v155, v54, v55
	v_pk_mul_f32 v[56:57], v[56:57], v[162:163] op_sel_hi:[1,0]
	v_pk_mul_f32 v[58:59], v[58:59], v[162:163] op_sel_hi:[1,0]
	v_pk_add_f32 v[72:73], v[72:73], 1.0 op_sel_hi:[1,0]
	v_pk_add_f32 v[74:75], v[74:75], 1.0 op_sel_hi:[1,0]
	v_pk_fma_f32 v[56:57], v[72:73], v[56:57], v[88:89]
	v_pk_fma_f32 v[58:59], v[74:75], v[58:59], v[90:91]
	v_cvt_pk_bf16_f32 v156, v56, v57
	v_cvt_pk_bf16_f32 v157, v58, v59
	v_pk_mul_f32 v[60:61], v[60:61], v[162:163] op_sel_hi:[1,0]
	v_pk_mul_f32 v[62:63], v[62:63], v[162:163] op_sel_hi:[1,0]
	v_pk_add_f32 v[76:77], v[76:77], 1.0 op_sel_hi:[1,0]
	v_pk_add_f32 v[78:79], v[78:79], 1.0 op_sel_hi:[1,0]
	v_pk_fma_f32 v[60:61], v[76:77], v[60:61], v[92:93]
	v_pk_fma_f32 v[62:63], v[78:79], v[62:63], v[94:95]
	v_cvt_pk_bf16_f32 v158, v60, v61
	v_cvt_pk_bf16_f32 v159, v62, v63
	global_store_dwordx2 v177, v[152:153], s[16:17]
	global_store_dwordx2 v177, v[154:155], s[16:17] offset:512
	global_store_dwordx2 v177, v[156:157], s[16:17] offset:1024
	global_store_dwordx2 v177, v[158:159], s[16:17] offset:1536
	s_add_i32 s19, s19, s1
	s_cmp_lt_u32 s19, 0x10000
	s_cselect_b32 s3, s19, s0
	s_sub_u32 s3, 0xffff, s3
	s_lshl_b32 s4, s3, 12
	s_add_u32 s6, s86, s4
	s_addc_u32 s7, s87, 0
	s_lshr_b32 s4, s3, 12
	s_mul_i32 s4, s4, 0x6000
	s_add_u32 s12, s88, s4
	s_addc_u32 s13, s89, 0
	s_add_u32 s14, s12, 0x104000
	s_addc_u32 s15, s13, 0
	s_add_u32 s12, s12, 0x103000
	s_addc_u32 s13, s13, 0
	global_load_dwordx4 v[48:51], v176, s[6:7]
	global_load_dwordx4 v[52:55], v176, s[6:7] offset:1024
	global_load_dwordx4 v[56:59], v176, s[6:7] offset:2048
	global_load_dwordx4 v[60:63], v176, s[6:7] offset:3072
	global_load_dwordx4 v[64:67], v176, s[14:15]
	global_load_dwordx4 v[68:71], v176, s[14:15] offset:1024
	global_load_dwordx4 v[72:75], v176, s[14:15] offset:2048
	global_load_dwordx4 v[76:79], v176, s[14:15] offset:3072
	global_load_dwordx4 v[80:83], v176, s[12:13]
	global_load_dwordx4 v[84:87], v176, s[12:13] offset:1024
	global_load_dwordx4 v[88:91], v176, s[12:13] offset:2048
	global_load_dwordx4 v[92:95], v176, s[12:13] offset:3072
	s_cmp_lt_u32 s20, 0x10000
	s_cbranch_scc0 .LNa_done
; __device__ __forceinline__ unsigned cvt_pk_bf16(float lo, float hi) { unsigned r; asm volatile("v_cvt_pk_bf16_f32 %0, %1, %2" : "=v"(r) : "v"(lo), "v"(hi)); return r; }
; __device__ __forceinline__ void phase_norm_mod(const float* x, const float* mod_shift, const float* mod_scale, bf16_t* H, int) {
;     ...
;         for (int r = 0; r < NR; ++r) { const int m = M - 1 - (m0 + r * NGW < M ? m0 + r * NGW : m0); const f32x4* xr = (const f32x4*)(x + (size_t)m * D) + lane;
; #pragma unroll
;             for (int j = 0; j < 4; ++j) v[r][j] = xr[64 * j]; }
; #pragma unroll
;         for (int r = 0; r < NR; ++r) { const int m = M - 1 - (m0 + r * NGW); if (m >= 0) {
;             const int b = m >> 12; float s = 0.f;
; #pragma unroll
;             for (int j = 0; j < 4; ++j) s += (v[r][j].x * v[r][j].x + v[r][j].y * v[r][j].y) + (v[r][j].z * v[r][j].z + v[r][j].w * v[r][j].w);
;             const float rstd = 1.0f / sqrtf(wave_sum(s) * (1.f / D) + 1e-6f);
;             const f32x4* sh = (const f32x4*)(mod_shift + (size_t)b * 6144) + lane;
;             const f32x4* sc = (const f32x4*)(mod_scale + (size_t)b * 6144) + lane;
;             u32x2* o = (u32x2*)(H + (size_t)m * D) + lane;
; #pragma unroll
;             for (int j = 0; j < 4; ++j) { const f32x4 a = sh[64 * j], c = sc[64 * j]; const f32x4 h = v[r][j] * rstd * (c + 1.0f) + a;
;                 u32x2 w; w.x = cvt_pk_bf16(h.x, h.y); w.y = cvt_pk_bf16(h.z, h.w); o[64 * j] = w; } } }
	s_waitcnt vmcnt(24)
	v_pk_mul_f32 v[172:173], v[96:97], v[96:97]
	v_pk_mul_f32 v[174:175], v[98:99], v[98:99]
	v_pk_fma_f32 v[172:173], v[100:101], v[100:101], v[172:173]
	v_pk_fma_f32 v[174:175], v[102:103], v[102:103], v[174:175]
	v_pk_fma_f32 v[172:173], v[104:105], v[104:105], v[172:173]
	v_pk_fma_f32 v[174:175], v[106:107], v[106:107], v[174:175]
	v_pk_fma_f32 v[172:173], v[108:109], v[108:109], v[172:173]
	v_pk_fma_f32 v[174:175], v[110:111], v[110:111], v[174:175]
	v_pk_add_f32 v[172:173], v[172:173], v[174:175]
	s_sub_u32 s3, 0xffff, s20
	s_lshl_b32 s4, s3, 11
	v_add_f32_e32 v160, v172, v173
	s_add_u32 s16, s88, s4
	s_addc_u32 s17, s89, 0
	s_nop 1
	v_add_f32_dpp v160, v160, v160 quad_perm:[1,0,3,2] row_mask:0xf bank_mask:0xf bound_ctrl:1
	s_nop 1
	v_add_f32_dpp v160, v160, v160 quad_perm:[2,3,0,1] row_mask:0xf bank_mask:0xf bound_ctrl:1
	s_nop 1
	v_add_f32_dpp v160, v160, v160 row_half_mirror row_mask:0xf bank_mask:0xf bound_ctrl:1
	s_nop 1
	v_add_f32_dpp v160, v160, v160 row_mirror row_mask:0xf bank_mask:0xf bound_ctrl:1
	s_add_u32 s16, s16, 0x3c00000
	s_addc_u32 s17, s17, 0
	v_readlane_b32 s4, v160, 0
	v_readlane_b32 s5, v160, 16
	v_readlane_b32 s3, v160, 32
	s_nop 1
	v_mov_b32_e32 v161, s4
	v_add_f32_e32 v161, s5, v161
	v_readlane_b32 s4, v160, 48
	v_add_f32_e32 v161, s3, v161
	s_nop 1
	v_add_f32_e32 v160, s4, v161
	v_fmamk_f32 v160, v160, 0x3a800000, v170
	v_mul_f32_e32 v161, 0x4f800000, v160
	v_cmp_gt_f32_e32 vcc, v178, v160
	s_nop 1
	v_cndmask_b32_e32 v162, v160, v161, vcc
	v_sqrt_f32_e32 v164, v162
	s_nop 0
	v_add_u32_e32 v165, -1, v164
	v_add_u32_e32 v166, 1, v164
	v_fma_f32 v167, -v165, v164, v162
	v_fma_f32 v168, -v166, v164, v162
	v_cmp_ge_f32_e64 s[4:5], 0, v167
	s_nop 1
	v_cndmask_b32_e64 v164, v164, v165, s[4:5]
	v_cmp_lt_f32_e64 s[4:5], 0, v168
	s_nop 1
	v_cndmask_b32_e64 v164, v164, v166, s[4:5]
	v_mul_f32_e32 v165, 0x37800000, v164
	v_cndmask_b32_e32 v164, v164, v165, vcc
	v_cmp_class_f32_e32 vcc, v162, v171
	s_nop 1
	v_cndmask_b32_e32 v162, v164, v162, vcc
	v_div_scale_f32 v164, s[4:5], v162, v162, 1.0
	v_rcp_f32_e32 v165, v164
	v_div_scale_f32 v166, vcc, 1.0, v162, 1.0
	v_fma_f32 v167, -v164, v165, 1.0
	v_fmac_f32_e32 v165, v167, v165
	v_mul_f32_e32 v167, v166, v165
	v_fma_f32 v168, -v164, v167, v166
	v_fmac_f32_e32 v167, v168, v165
	v_fma_f32 v164, -v164, v167, v166
	v_div_fmas_f32 v164, v164, v165, v167
	v_div_fixup_f32 v162, v164, v162, 1.0
	v_pk_mul_f32 v[96:97], v[96:97], v[162:163] op_sel_hi:[1,0]
	v_pk_mul_f32 v[98:99], v[98:99], v[162:163] op_sel_hi:[1,0]
	v_pk_add_f32 v[112:113], v[112:113], 1.0 op_sel_hi:[1,0]
	v_pk_add_f32 v[114:115], v[114:115], 1.0 op_sel_hi:[1,0]
	v_pk_fma_f32 v[96:97], v[112:113], v[96:97], v[128:129]
	v_pk_fma_f32 v[98:99], v[114:115], v[98:99], v[130:131]
	v_cvt_pk_bf16_f32 v152, v96, v97
	v_cvt_pk_bf16_f32 v153, v98, v99
	v_pk_mul_f32 v[100:101], v[100:101], v[162:163] op_sel_hi:[1,0]
	v_pk_mul_f32 v[102:103], v[102:103], v[162:163] op_sel_hi:[1,0]
	v_pk_add_f32 v[116:117], v[116:117], 1.0 op_sel_hi:[1,0]
	v_pk_add_f32 v[118:119], v[118:119], 1.0 op_sel_hi:[1,0]
	v_pk_fma_f32 v[100:101], v[116:117], v[100:101], v[132:133]
	v_pk_fma_f32 v[102:103], v[118:119], v[102:103], v[134:135]
	v_cvt_pk_bf16_f32 v154, v100, v101
	v_cvt_pk_bf16_f32 v155, v102, v103
	v_pk_mul_f32 v[104:105], v[104:105], v[162:163] op_sel_hi:[1,0]
	v_pk_mul_f32 v[106:107], v[106:107], v[162:163] op_sel_hi:[1,0]
	v_pk_add_f32 v[120:121], v[120:121], 1.0 op_sel_hi:[1,0]
	v_pk_add_f32 v[122:123], v[122:123], 1.0 op_sel_hi:[1,0]
	v_pk_fma_f32 v[104:105], v[120:121], v[104:105], v[136:137]
	v_pk_fma_f32 v[106:107], v[122:123], v[106:107], v[138:139]
	v_cvt_pk_bf16_f32 v156, v104, v105
	v_cvt_pk_bf16_f32 v157, v106, v107
	v_pk_mul_f32 v[108:109], v[108:109], v[162:163] op_sel_hi:[1,0]
	v_pk_mul_f32 v[110:111], v[110:111], v[162:163] op_sel_hi:[1,0]
	v_pk_add_f32 v[124:125], v[124:125], 1.0 op_sel_hi:[1,0]
	v_pk_add_f32 v[126:127], v[126:127], 1.0 op_sel_hi:[1,0]
	v_pk_fma_f32 v[108:109], v[124:125], v[108:109], v[140:141]
	v_pk_fma_f32 v[110:111], v[126:127], v[110:111], v[142:143]
	v_cvt_pk_bf16_f32 v158, v108, v109
	v_cvt_pk_bf16_f32 v159, v110, v111
	global_store_dwordx2 v177, v[152:153], s[16:17]
	global_store_dwordx2 v177, v[154:155], s[16:17] offset:512
	global_store_dwordx2 v177, v[156:157], s[16:17] offset:1024
	global_store_dwordx2 v177, v[158:159], s[16:17] offset:1536
	s_add_i32 s20, s20, s1
	s_cmp_lt_u32 s20, 0x10000
	s_cselect_b32 s3, s20, s0
	s_sub_u32 s3, 0xffff, s3
	s_lshl_b32 s4, s3, 12
	s_add_u32 s6, s86, s4
	s_addc_u32 s7, s87, 0
	s_lshr_b32 s4, s3, 12
	s_mul_i32 s4, s4, 0x6000
	s_add_u32 s12, s88, s4
	s_addc_u32 s13, s89, 0
	s_add_u32 s14, s12, 0x104000
	s_addc_u32 s15, s13, 0
	s_add_u32 s12, s12, 0x103000
	s_addc_u32 s13, s13, 0
	global_load_dwordx4 v[96:99], v176, s[6:7]
	global_load_dwordx4 v[100:103], v176, s[6:7] offset:1024
	global_load_dwordx4 v[104:107], v176, s[6:7] offset:2048
	global_load_dwordx4 v[108:111], v176, s[6:7] offset:3072
	global_load_dwordx4 v[112:115], v176, s[14:15]
	global_load_dwordx4 v[116:119], v176, s[14:15] offset:1024
	global_load_dwordx4 v[120:123], v176, s[14:15] offset:2048
	global_load_dwordx4 v[124:127], v176, s[14:15] offset:3072
	global_load_dwordx4 v[128:131], v176, s[12:13]
	global_load_dwordx4 v[132:135], v176, s[12:13] offset:1024
	global_load_dwordx4 v[136:139], v176, s[12:13] offset:2048
	global_load_dwordx4 v[140:143], v176, s[12:13] offset:3072
	s_branch .LNa_loop

; __device__ __forceinline__ int opaque_tid() { int t = threadIdx.x; asm volatile("" : "+v"(t)); return t; }
; __device__ __forceinline__ unsigned cvt_pk_bf16(float lo, float hi) { unsigned r; asm volatile("v_cvt_pk_bf16_f32 %0, %1, %2" : "=v"(r) : "v"(lo), "v"(hi)); return r; }
; __device__ __forceinline__ void phase_norm_mod(const float* x, const float* mod_shift, const float* mod_scale, bf16_t* H, int) {
;     const int tid = opaque_tid(), lane = tid & 63, wave = tid >> 6;
;     const int gw = blockIdx.x * NWAVES + wave, NGW = gridDim.x * NWAVES;
;     constexpr int NR = 4;
;     for (int m0 = gw; m0 < M; m0 += NR * NGW) {
;         f32x4 v[NR][4];
; #pragma unroll
;         for (int r = 0; r < NR; ++r) { const int m = M - 1 - (m0 + r * NGW < M ? m0 + r * NGW : m0); const f32x4* xr = (const f32x4*)(x + (size_t)m * D) + lane;
; #pragma unroll
;             for (int j = 0; j < 4; ++j) v[r][j] = xr[64 * j]; }
; #pragma unroll
;         for (int r = 0; r < NR; ++r) { const int m = M - 1 - (m0 + r * NGW); if (m >= 0) {
;             const int b = m >> 12; float s = 0.f;
; #pragma unroll
;             for (int j = 0; j < 4; ++j) s += (v[r][j].x * v[r][j].x + v[r][j].y * v[r][j].y) + (v[r][j].z * v[r][j].z + v[r][j].w * v[r][j].w);
;             const float rstd = 1.0f / sqrtf(wave_sum(s) * (1.f / D) + 1e-6f);
;             const f32x4* sh = (const f32x4*)(mod_shift + (size_t)b * 6144) + lane;
;             const f32x4* sc = (const f32x4*)(mod_scale + (size_t)b * 6144) + lane;
;             u32x2* o = (u32x2*)(H + (size_t)m * D) + lane;
; #pragma unroll
;             for (int j = 0; j < 4; ++j) { const f32x4 a = sh[64 * j], c = sc[64 * j]; const f32x4 h = v[r][j] * rstd * (c + 1.0f) + a;
;                 u32x2 w; w.x = cvt_pk_bf16(h.x, h.y); w.y = cvt_pk_bf16(h.z, h.w); o[64 * j] = w; } } }
; template <int l> __device__ __forceinline__ void layer(const Args& a, LAS unsigned char* lds, cg::grid_group& grid, const XcdBarrier& xbar, int& ph, const int lo, const int hi) {
;     ...
;     if (RUN) phase_norm_mod(a.out, mod + 3 * 1024, mod + 4 * 1024, H, 0);
.LBB0_2203:
	s_cmp_lt_i32 s90, 13
	s_cselect_b64 s[8:9], -1, 0
	s_and_b64 s[0:1], s[8:9], s[0:1]
	s_andn2_b64 vcc, exec, s[0:1]
	s_cbranch_vccnz .LBB0_2214
	s_mov_b64 s[10:11], exec
	v_mov_b32_e32 v178, 0xf800000
	v_lshrrev_b32_e32 v176, 6, v180
	v_and_b32_e32 v177, 63, v180
	v_readfirstlane_b32 s0, v176
	v_lshlrev_b32_e32 v176, 4, v177
	v_lshlrev_b32_e32 v177, 3, v177
	v_mov_b32_e32 v170, 0x358637bd
	v_mov_b32_e32 v171, 0x260
	s_lshl_b32 s1, s24, 3
	s_add_i32 s0, s0, s1
	s_lshl_b32 s2, s28, 3
	s_mul_i32 s1, s2, 3
	s_mov_b32 s18, s0
	s_add_i32 s19, s0, s2
	s_add_i32 s20, s19, s2
	s_cmp_lt_u32 s0, 0x10000
	s_cbranch_scc0 .LNb_done
	s_cmp_lt_u32 s18, 0x10000
	s_cselect_b32 s3, s18, s0
	s_sub_u32 s3, 0xffff, s3
	s_lshl_b32 s4, s3, 12
	s_add_u32 s6, s86, s4
	s_addc_u32 s7, s87, 0
	s_lshr_b32 s4, s3, 12
	s_mul_i32 s4, s4, 0x6000
	s_add_u32 s12, s88, s4
	s_addc_u32 s13, s89, 0
	s_add_u32 s14, s12, 0x164000
	s_addc_u32 s15, s13, 0
	s_add_u32 s12, s12, 0x163000
	s_addc_u32 s13, s13, 0
	global_load_dwordx4 v[0:3], v176, s[6:7]
	global_load_dwordx4 v[4:7], v176, s[6:7] offset:1024
	global_load_dwordx4 v[8:11], v176, s[6:7] offset:2048
	global_load_dwordx4 v[12:15], v176, s[6:7] offset:3072
	global_load_dwordx4 v[16:19], v176, s[14:15]
	global_load_dwordx4 v[20:23], v176, s[14:15] offset:1024
	global_load_dwordx4 v[24:27], v176, s[14:15] offset:2048
	global_load_dwordx4 v[28:31], v176, s[14:15] offset:3072
	global_load_dwordx4 v[32:35], v176, s[12:13]
	global_load_dwordx4 v[36:39], v176, s[12:13] offset:1024
	global_load_dwordx4 v[40:43], v176, s[12:13] offset:2048
	global_load_dwordx4 v[44:47], v176, s[12:13] offset:3072
	s_cmp_lt_u32 s19, 0x10000
	s_cselect_b32 s3, s19, s0
	s_sub_u32 s3, 0xffff, s3
	s_lshl_b32 s4, s3, 12
	s_add_u32 s6, s86, s4
	s_addc_u32 s7, s87, 0
	s_lshr_b32 s4, s3, 12
	s_mul_i32 s4, s4, 0x6000
	s_add_u32 s12, s88, s4
	s_addc_u32 s13, s89, 0
	s_add_u32 s14, s12, 0x164000
	s_addc_u32 s15, s13, 0
	s_add_u32 s12, s12, 0x163000
	s_addc_u32 s13, s13, 0
	global_load_dwordx4 v[48:51], v176, s[6:7]
	global_load_dwordx4 v[52:55], v176, s[6:7] offset:1024
	global_load_dwordx4 v[56:59], v176, s[6:7] offset:2048
	global_load_dwordx4 v[60:63], v176, s[6:7] offset:3072
	global_load_dwordx4 v[64:67], v176, s[14:15]
	global_load_dwordx4 v[68:71], v176, s[14:15] offset:1024
	global_load_dwordx4 v[72:75], v176, s[14:15] offset:2048
	global_load_dwordx4 v[76:79], v176, s[14:15] offset:3072
	global_load_dwordx4 v[80:83], v176, s[12:13]
	global_load_dwordx4 v[84:87], v176, s[12:13] offset:1024
	global_load_dwordx4 v[88:91], v176, s[12:13] offset:2048
	global_load_dwordx4 v[92:95], v176, s[12:13] offset:3072
	s_cmp_lt_u32 s20, 0x10000
	s_cselect_b32 s3, s20, s0
	s_sub_u32 s3, 0xffff, s3
	s_lshl_b32 s4, s3, 12
	s_add_u32 s6, s86, s4
	s_addc_u32 s7, s87, 0
	s_lshr_b32 s4, s3, 12
	s_mul_i32 s4, s4, 0x6000
	s_add_u32 s12, s88, s4
	s_addc_u32 s13, s89, 0
	s_add_u32 s14, s12, 0x164000
	s_addc_u32 s15, s13, 0
	s_add_u32 s12, s12, 0x163000
	s_addc_u32 s13, s13, 0
	global_load_dwordx4 v[96:99], v176, s[6:7]
	global_load_dwordx4 v[100:103], v176, s[6:7] offset:1024
	global_load_dwordx4 v[104:107], v176, s[6:7] offset:2048
	global_load_dwordx4 v[108:111], v176, s[6:7] offset:3072
	global_load_dwordx4 v[112:115], v176, s[14:15]
	global_load_dwordx4 v[116:119], v176, s[14:15] offset:1024
	global_load_dwordx4 v[120:123], v176, s[14:15] offset:2048
	global_load_dwordx4 v[124:127], v176, s[14:15] offset:3072
	global_load_dwordx4 v[128:131], v176, s[12:13]
	global_load_dwordx4 v[132:135], v176, s[12:13] offset:1024
	global_load_dwordx4 v[136:139], v176, s[12:13] offset:2048
	global_load_dwordx4 v[140:143], v176, s[12:13] offset:3072
.LNb_loop:
	s_cmp_lt_u32 s18, 0x10000
	s_cbranch_scc0 .LNb_done
	s_waitcnt vmcnt(24)
	v_pk_mul_f32 v[172:173], v[0:1], v[0:1]
	v_pk_mul_f32 v[174:175], v[2:3], v[2:3]
	v_pk_fma_f32 v[172:173], v[4:5], v[4:5], v[172:173]
	v_pk_fma_f32 v[174:175], v[6:7], v[6:7], v[174:175]
	v_pk_fma_f32 v[172:173], v[8:9], v[8:9], v[172:173]
	v_pk_fma_f32 v[174:175], v[10:11], v[10:11], v[174:175]
	v_pk_fma_f32 v[172:173], v[12:13], v[12:13], v[172:173]
	v_pk_fma_f32 v[174:175], v[14:15], v[14:15], v[174:175]
	v_pk_add_f32 v[172:173], v[172:173], v[174:175]
	s_sub_u32 s3, 0xffff, s18
	s_lshl_b32 s4, s3, 11
	v_add_f32_e32 v160, v172, v173
	s_add_u32 s16, s88, s4
	s_addc_u32 s17, s89, 0
	s_nop 1
	v_add_f32_dpp v160, v160, v160 quad_perm:[1,0,3,2] row_mask:0xf bank_mask:0xf bound_ctrl:1
	s_nop 1
	v_add_f32_dpp v160, v160, v160 quad_perm:[2,3,0,1] row_mask:0xf bank_mask:0xf bound_ctrl:1
	s_nop 1
	v_add_f32_dpp v160, v160, v160 row_half_mirror row_mask:0xf bank_mask:0xf bound_ctrl:1
	s_nop 1
	v_add_f32_dpp v160, v160, v160 row_mirror row_mask:0xf bank_mask:0xf bound_ctrl:1
	s_add_u32 s16, s16, 0x3c00000
	s_addc_u32 s17, s17, 0
	v_readlane_b32 s4, v160, 0
	v_readlane_b32 s5, v160, 16
	v_readlane_b32 s3, v160, 32
	s_nop 1
	v_mov_b32_e32 v161, s4
	v_add_f32_e32 v161, s5, v161
	v_readlane_b32 s4, v160, 48
	v_add_f32_e32 v161, s3, v161
	s_nop 1
	v_add_f32_e32 v160, s4, v161
	v_fmamk_f32 v160, v160, 0x3a800000, v170
	v_mul_f32_e32 v161, 0x4f800000, v160
	v_cmp_gt_f32_e32 vcc, v178, v160
	s_nop 1
	v_cndmask_b32_e32 v162, v160, v161, vcc
	v_sqrt_f32_e32 v164, v162
	s_nop 0
	v_add_u32_e32 v165, -1, v164
	v_add_u32_e32 v166, 1, v164
	v_fma_f32 v167, -v165, v164, v162
	v_fma_f32 v168, -v166, v164, v162
	v_cmp_ge_f32_e64 s[4:5], 0, v167
	s_nop 1
	v_cndmask_b32_e64 v164, v164, v165, s[4:5]
	v_cmp_lt_f32_e64 s[4:5], 0, v168
	s_nop 1
	v_cndmask_b32_e64 v164, v164, v166, s[4:5]
	v_mul_f32_e32 v165, 0x37800000, v164
	v_cndmask_b32_e32 v164, v164, v165, vcc
; __device__ __forceinline__ unsigned cvt_pk_bf16(float lo, float hi) { unsigned r; asm volatile("v_cvt_pk_bf16_f32 %0, %1, %2" : "=v"(r) : "v"(lo), "v"(hi)); return r; }
; __device__ __forceinline__ void phase_norm_mod(const float* x, const float* mod_shift, const float* mod_scale, bf16_t* H, int) {
;     ...
;         for (int r = 0; r < NR; ++r) { const int m = M - 1 - (m0 + r * NGW < M ? m0 + r * NGW : m0); const f32x4* xr = (const f32x4*)(x + (size_t)m * D) + lane;
; #pragma unroll
;             for (int j = 0; j < 4; ++j) v[r][j] = xr[64 * j]; }
; #pragma unroll
;         for (int r = 0; r < NR; ++r) { const int m = M - 1 - (m0 + r * NGW); if (m >= 0) {
;             const int b = m >> 12; float s = 0.f;
; #pragma unroll
;             for (int j = 0; j < 4; ++j) s += (v[r][j].x * v[r][j].x + v[r][j].y * v[r][j].y) + (v[r][j].z * v[r][j].z + v[r][j].w * v[r][j].w);
;             const float rstd = 1.0f / sqrtf(wave_sum(s) * (1.f / D) + 1e-6f);
;             const f32x4* sh = (const f32x4*)(mod_shift + (size_t)b * 6144) + lane;
;             const f32x4* sc = (const f32x4*)(mod_scale + (size_t)b * 6144) + lane;
;             u32x2* o = (u32x2*)(H + (size_t)m * D) + lane;
; #pragma unroll
;             for (int j = 0; j < 4; ++j) { const f32x4 a = sh[64 * j], c = sc[64 * j]; const f32x4 h = v[r][j] * rstd * (c + 1.0f) + a;
;                 u32x2 w; w.x = cvt_pk_bf16(h.x, h.y); w.y = cvt_pk_bf16(h.z, h.w); o[64 * j] = w; } } }
	v_cmp_class_f32_e32 vcc, v162, v171
	s_nop 1
	v_cndmask_b32_e32 v162, v164, v162, vcc
	v_div_scale_f32 v164, s[4:5], v162, v162, 1.0
	v_rcp_f32_e32 v165, v164
	v_div_scale_f32 v166, vcc, 1.0, v162, 1.0
	v_fma_f32 v167, -v164, v165, 1.0
	v_fmac_f32_e32 v165, v167, v165
	v_mul_f32_e32 v167, v166, v165
	v_fma_f32 v168, -v164, v167, v166
	v_fmac_f32_e32 v167, v168, v165
	v_fma_f32 v164, -v164, v167, v166
	v_div_fmas_f32 v164, v164, v165, v167
	v_div_fixup_f32 v162, v164, v162, 1.0
	v_pk_mul_f32 v[0:1], v[0:1], v[162:163] op_sel_hi:[1,0]
	v_pk_mul_f32 v[2:3], v[2:3], v[162:163] op_sel_hi:[1,0]
	v_pk_add_f32 v[16:17], v[16:17], 1.0 op_sel_hi:[1,0]
	v_pk_add_f32 v[18:19], v[18:19], 1.0 op_sel_hi:[1,0]
	v_pk_fma_f32 v[0:1], v[16:17], v[0:1], v[32:33]
	v_pk_fma_f32 v[2:3], v[18:19], v[2:3], v[34:35]
	v_cvt_pk_bf16_f32 v152, v0, v1
	v_cvt_pk_bf16_f32 v153, v2, v3
	v_pk_mul_f32 v[4:5], v[4:5], v[162:163] op_sel_hi:[1,0]
	v_pk_mul_f32 v[6:7], v[6:7], v[162:163] op_sel_hi:[1,0]
	v_pk_add_f32 v[20:21], v[20:21], 1.0 op_sel_hi:[1,0]
	v_pk_add_f32 v[22:23], v[22:23], 1.0 op_sel_hi:[1,0]
	v_pk_fma_f32 v[4:5], v[20:21], v[4:5], v[36:37]
	v_pk_fma_f32 v[6:7], v[22:23], v[6:7], v[38:39]
	v_cvt_pk_bf16_f32 v154, v4, v5
	v_cvt_pk_bf16_f32 v155, v6, v7
	v_pk_mul_f32 v[8:9], v[8:9], v[162:163] op_sel_hi:[1,0]
	v_pk_mul_f32 v[10:11], v[10:11], v[162:163] op_sel_hi:[1,0]
	v_pk_add_f32 v[24:25], v[24:25], 1.0 op_sel_hi:[1,0]
	v_pk_add_f32 v[26:27], v[26:27], 1.0 op_sel_hi:[1,0]
	v_pk_fma_f32 v[8:9], v[24:25], v[8:9], v[40:41]
	v_pk_fma_f32 v[10:11], v[26:27], v[10:11], v[42:43]
	v_cvt_pk_bf16_f32 v156, v8, v9
	v_cvt_pk_bf16_f32 v157, v10, v11
	v_pk_mul_f32 v[12:13], v[12:13], v[162:163] op_sel_hi:[1,0]
	v_pk_mul_f32 v[14:15], v[14:15], v[162:163] op_sel_hi:[1,0]
	v_pk_add_f32 v[28:29], v[28:29], 1.0 op_sel_hi:[1,0]
	v_pk_add_f32 v[30:31], v[30:31], 1.0 op_sel_hi:[1,0]
	v_pk_fma_f32 v[12:13], v[28:29], v[12:13], v[44:45]
	v_pk_fma_f32 v[14:15], v[30:31], v[14:15], v[46:47]
	v_cvt_pk_bf16_f32 v158, v12, v13
	v_cvt_pk_bf16_f32 v159, v14, v15
	global_store_dwordx2 v177, v[152:153], s[16:17]
	global_store_dwordx2 v177, v[154:155], s[16:17] offset:512
	global_store_dwordx2 v177, v[156:157], s[16:17] offset:1024
	global_store_dwordx2 v177, v[158:159], s[16:17] offset:1536
	s_add_i32 s18, s18, s1
	s_cmp_lt_u32 s18, 0x10000
	s_cselect_b32 s3, s18, s0
	s_sub_u32 s3, 0xffff, s3
	s_lshl_b32 s4, s3, 12
	s_add_u32 s6, s86, s4
	s_addc_u32 s7, s87, 0
	s_lshr_b32 s4, s3, 12
	s_mul_i32 s4, s4, 0x6000
	s_add_u32 s12, s88, s4
	s_addc_u32 s13, s89, 0
	s_add_u32 s14, s12, 0x164000
	s_addc_u32 s15, s13, 0
	s_add_u32 s12, s12, 0x163000
	s_addc_u32 s13, s13, 0
	global_load_dwordx4 v[0:3], v176, s[6:7]
	global_load_dwordx4 v[4:7], v176, s[6:7] offset:1024
	global_load_dwordx4 v[8:11], v176, s[6:7] offset:2048
	global_load_dwordx4 v[12:15], v176, s[6:7] offset:3072
	global_load_dwordx4 v[16:19], v176, s[14:15]
	global_load_dwordx4 v[20:23], v176, s[14:15] offset:1024
	global_load_dwordx4 v[24:27], v176, s[14:15] offset:2048
	global_load_dwordx4 v[28:31], v176, s[14:15] offset:3072
	global_load_dwordx4 v[32:35], v176, s[12:13]
	global_load_dwordx4 v[36:39], v176, s[12:13] offset:1024
	global_load_dwordx4 v[40:43], v176, s[12:13] offset:2048
	global_load_dwordx4 v[44:47], v176, s[12:13] offset:3072
	s_cmp_lt_u32 s19, 0x10000
	s_cbranch_scc0 .LNb_done
	s_waitcnt vmcnt(24)
	v_pk_mul_f32 v[172:173], v[48:49], v[48:49]
	v_pk_mul_f32 v[174:175], v[50:51], v[50:51]
	v_pk_fma_f32 v[172:173], v[52:53], v[52:53], v[172:173]
	v_pk_fma_f32 v[174:175], v[54:55], v[54:55], v[174:175]
	v_pk_fma_f32 v[172:173], v[56:57], v[56:57], v[172:173]
	v_pk_fma_f32 v[174:175], v[58:59], v[58:59], v[174:175]
	v_pk_fma_f32 v[172:173], v[60:61], v[60:61], v[172:173]
	v_pk_fma_f32 v[174:175], v[62:63], v[62:63], v[174:175]
	v_pk_add_f32 v[172:173], v[172:173], v[174:175]
	s_sub_u32 s3, 0xffff, s19
	s_lshl_b32 s4, s3, 11
	v_add_f32_e32 v160, v172, v173
	s_add_u32 s16, s88, s4
	s_addc_u32 s17, s89, 0
	s_nop 1
	v_add_f32_dpp v160, v160, v160 quad_perm:[1,0,3,2] row_mask:0xf bank_mask:0xf bound_ctrl:1
	s_nop 1
	v_add_f32_dpp v160, v160, v160 quad_perm:[2,3,0,1] row_mask:0xf bank_mask:0xf bound_ctrl:1
	s_nop 1
	v_add_f32_dpp v160, v160, v160 row_half_mirror row_mask:0xf bank_mask:0xf bound_ctrl:1
	s_nop 1
	v_add_f32_dpp v160, v160, v160 row_mirror row_mask:0xf bank_mask:0xf bound_ctrl:1
	s_add_u32 s16, s16, 0x3c00000
	s_addc_u32 s17, s17, 0
	v_readlane_b32 s4, v160, 0
	v_readlane_b32 s5, v160, 16
	v_readlane_b32 s3, v160, 32
	s_nop 1
	v_mov_b32_e32 v161, s4
	v_add_f32_e32 v161, s5, v161
	v_readlane_b32 s4, v160, 48
	v_add_f32_e32 v161, s3, v161
	s_nop 1
	v_add_f32_e32 v160, s4, v161
	v_fmamk_f32 v160, v160, 0x3a800000, v170
	v_mul_f32_e32 v161, 0x4f800000, v160
	v_cmp_gt_f32_e32 vcc, v178, v160
	s_nop 1
	v_cndmask_b32_e32 v162, v160, v161, vcc
	v_sqrt_f32_e32 v164, v162
	s_nop 0
	v_add_u32_e32 v165, -1, v164
	v_add_u32_e32 v166, 1, v164
	v_fma_f32 v167, -v165, v164, v162
	v_fma_f32 v168, -v166, v164, v162
	v_cmp_ge_f32_e64 s[4:5], 0, v167
	s_nop 1
	v_cndmask_b32_e64 v164, v164, v165, s[4:5]
	v_cmp_lt_f32_e64 s[4:5], 0, v168
	s_nop 1
	v_cndmask_b32_e64 v164, v164, v166, s[4:5]
	v_mul_f32_e32 v165, 0x37800000, v164
	v_cndmask_b32_e32 v164, v164, v165, vcc
	v_cmp_class_f32_e32 vcc, v162, v171
	s_nop 1
	v_cndmask_b32_e32 v162, v164, v162, vcc
	v_div_scale_f32 v164, s[4:5], v162, v162, 1.0
	v_rcp_f32_e32 v165, v164
	v_div_scale_f32 v166, vcc, 1.0, v162, 1.0
	v_fma_f32 v167, -v164, v165, 1.0
	v_fmac_f32_e32 v165, v167, v165
	v_mul_f32_e32 v167, v166, v165
	v_fma_f32 v168, -v164, v167, v166
	v_fmac_f32_e32 v167, v168, v165
; __device__ __forceinline__ unsigned cvt_pk_bf16(float lo, float hi) { unsigned r; asm volatile("v_cvt_pk_bf16_f32 %0, %1, %2" : "=v"(r) : "v"(lo), "v"(hi)); return r; }
; __device__ __forceinline__ void phase_norm_mod(const float* x, const float* mod_shift, const float* mod_scale, bf16_t* H, int) {
;     ...
;         for (int r = 0; r < NR; ++r) { const int m = M - 1 - (m0 + r * NGW < M ? m0 + r * NGW : m0); const f32x4* xr = (const f32x4*)(x + (size_t)m * D) + lane;
; #pragma unroll
;             for (int j = 0; j < 4; ++j) v[r][j] = xr[64 * j]; }
; #pragma unroll
;         for (int r = 0; r < NR; ++r) { const int m = M - 1 - (m0 + r * NGW); if (m >= 0) {
;             const int b = m >> 12; float s = 0.f;
; #pragma unroll
;             for (int j = 0; j < 4; ++j) s += (v[r][j].x * v[r][j].x + v[r][j].y * v[r][j].y) + (v[r][j].z * v[r][j].z + v[r][j].w * v[r][j].w);
;             const float rstd = 1.0f / sqrtf(wave_sum(s) * (1.f / D) + 1e-6f);
;             const f32x4* sh = (const f32x4*)(mod_shift + (size_t)b * 6144) + lane;
;             const f32x4* sc = (const f32x4*)(mod_scale + (size_t)b * 6144) + lane;
;             u32x2* o = (u32x2*)(H + (size_t)m * D) + lane;
; #pragma unroll
;             for (int j = 0; j < 4; ++j) { const f32x4 a = sh[64 * j], c = sc[64 * j]; const f32x4 h = v[r][j] * rstd * (c + 1.0f) + a;
;                 u32x2 w; w.x = cvt_pk_bf16(h.x, h.y); w.y = cvt_pk_bf16(h.z, h.w); o[64 * j] = w; } } }
	v_fma_f32 v164, -v164, v167, v166
	v_div_fmas_f32 v164, v164, v165, v167
	v_div_fixup_f32 v162, v164, v162, 1.0
	v_pk_mul_f32 v[48:49], v[48:49], v[162:163] op_sel_hi:[1,0]
	v_pk_mul_f32 v[50:51], v[50:51], v[162:163] op_sel_hi:[1,0]
	v_pk_add_f32 v[64:65], v[64:65], 1.0 op_sel_hi:[1,0]
	v_pk_add_f32 v[66:67], v[66:67], 1.0 op_sel_hi:[1,0]
	v_pk_fma_f32 v[48:49], v[64:65], v[48:49], v[80:81]
	v_pk_fma_f32 v[50:51], v[66:67], v[50:51], v[82:83]
	v_cvt_pk_bf16_f32 v152, v48, v49
	v_cvt_pk_bf16_f32 v153, v50, v51
	v_pk_mul_f32 v[52:53], v[52:53], v[162:163] op_sel_hi:[1,0]
	v_pk_mul_f32 v[54:55], v[54:55], v[162:163] op_sel_hi:[1,0]
	v_pk_add_f32 v[68:69], v[68:69], 1.0 op_sel_hi:[1,0]
	v_pk_add_f32 v[70:71], v[70:71], 1.0 op_sel_hi:[1,0]
	v_pk_fma_f32 v[52:53], v[68:69], v[52:53], v[84:85]
	v_pk_fma_f32 v[54:55], v[70:71], v[54:55], v[86:87]
	v_cvt_pk_bf16_f32 v154, v52, v53
	v_cvt_pk_bf16_f32 v155, v54, v55
	v_pk_mul_f32 v[56:57], v[56:57], v[162:163] op_sel_hi:[1,0]
	v_pk_mul_f32 v[58:59], v[58:59], v[162:163] op_sel_hi:[1,0]
	v_pk_add_f32 v[72:73], v[72:73], 1.0 op_sel_hi:[1,0]
	v_pk_add_f32 v[74:75], v[74:75], 1.0 op_sel_hi:[1,0]
	v_pk_fma_f32 v[56:57], v[72:73], v[56:57], v[88:89]
	v_pk_fma_f32 v[58:59], v[74:75], v[58:59], v[90:91]
	v_cvt_pk_bf16_f32 v156, v56, v57
	v_cvt_pk_bf16_f32 v157, v58, v59
	v_pk_mul_f32 v[60:61], v[60:61], v[162:163] op_sel_hi:[1,0]
	v_pk_mul_f32 v[62:63], v[62:63], v[162:163] op_sel_hi:[1,0]
	v_pk_add_f32 v[76:77], v[76:77], 1.0 op_sel_hi:[1,0]
	v_pk_add_f32 v[78:79], v[78:79], 1.0 op_sel_hi:[1,0]
	v_pk_fma_f32 v[60:61], v[76:77], v[60:61], v[92:93]
	v_pk_fma_f32 v[62:63], v[78:79], v[62:63], v[94:95]
	v_cvt_pk_bf16_f32 v158, v60, v61
	v_cvt_pk_bf16_f32 v159, v62, v63
	global_store_dwordx2 v177, v[152:153], s[16:17]
	global_store_dwordx2 v177, v[154:155], s[16:17] offset:512
	global_store_dwordx2 v177, v[156:157], s[16:17] offset:1024
	global_store_dwordx2 v177, v[158:159], s[16:17] offset:1536
	s_add_i32 s19, s19, s1
	s_cmp_lt_u32 s19, 0x10000
	s_cselect_b32 s3, s19, s0
	s_sub_u32 s3, 0xffff, s3
	s_lshl_b32 s4, s3, 12
	s_add_u32 s6, s86, s4
	s_addc_u32 s7, s87, 0
	s_lshr_b32 s4, s3, 12
	s_mul_i32 s4, s4, 0x6000
	s_add_u32 s12, s88, s4
	s_addc_u32 s13, s89, 0
	s_add_u32 s14, s12, 0x164000
	s_addc_u32 s15, s13, 0
	s_add_u32 s12, s12, 0x163000
	s_addc_u32 s13, s13, 0
	global_load_dwordx4 v[48:51], v176, s[6:7]
	global_load_dwordx4 v[52:55], v176, s[6:7] offset:1024
	global_load_dwordx4 v[56:59], v176, s[6:7] offset:2048
	global_load_dwordx4 v[60:63], v176, s[6:7] offset:3072
	global_load_dwordx4 v[64:67], v176, s[14:15]
	global_load_dwordx4 v[68:71], v176, s[14:15] offset:1024
	global_load_dwordx4 v[72:75], v176, s[14:15] offset:2048
	global_load_dwordx4 v[76:79], v176, s[14:15] offset:3072
	global_load_dwordx4 v[80:83], v176, s[12:13]
	global_load_dwordx4 v[84:87], v176, s[12:13] offset:1024
	global_load_dwordx4 v[88:91], v176, s[12:13] offset:2048
	global_load_dwordx4 v[92:95], v176, s[12:13] offset:3072
	s_cmp_lt_u32 s20, 0x10000
	s_cbranch_scc0 .LNb_done
; __device__ __forceinline__ unsigned cvt_pk_bf16(float lo, float hi) { unsigned r; asm volatile("v_cvt_pk_bf16_f32 %0, %1, %2" : "=v"(r) : "v"(lo), "v"(hi)); return r; }
; __device__ __forceinline__ void phase_norm_mod(const float* x, const float* mod_shift, const float* mod_scale, bf16_t* H, int) {
;     ...
;         for (int r = 0; r < NR; ++r) { const int m = M - 1 - (m0 + r * NGW < M ? m0 + r * NGW : m0); const f32x4* xr = (const f32x4*)(x + (size_t)m * D) + lane;
; #pragma unroll
;             for (int j = 0; j < 4; ++j) v[r][j] = xr[64 * j]; }
; #pragma unroll
;         for (int r = 0; r < NR; ++r) { const int m = M - 1 - (m0 + r * NGW); if (m >= 0) {
;             const int b = m >> 12; float s = 0.f;
; #pragma unroll
;             for (int j = 0; j < 4; ++j) s += (v[r][j].x * v[r][j].x + v[r][j].y * v[r][j].y) + (v[r][j].z * v[r][j].z + v[r][j].w * v[r][j].w);
;             const float rstd = 1.0f / sqrtf(wave_sum(s) * (1.f / D) + 1e-6f);
;             const f32x4* sh = (const f32x4*)(mod_shift + (size_t)b * 6144) + lane;
;             const f32x4* sc = (const f32x4*)(mod_scale + (size_t)b * 6144) + lane;
;             u32x2* o = (u32x2*)(H + (size_t)m * D) + lane;
; #pragma unroll
;             for (int j = 0; j < 4; ++j) { const f32x4 a = sh[64 * j], c = sc[64 * j]; const f32x4 h = v[r][j] * rstd * (c + 1.0f) + a;
;                 u32x2 w; w.x = cvt_pk_bf16(h.x, h.y); w.y = cvt_pk_bf16(h.z, h.w); o[64 * j] = w; } } }
	s_waitcnt vmcnt(24)
	v_pk_mul_f32 v[172:173], v[96:97], v[96:97]
	v_pk_mul_f32 v[174:175], v[98:99], v[98:99]
	v_pk_fma_f32 v[172:173], v[100:101], v[100:101], v[172:173]
	v_pk_fma_f32 v[174:175], v[102:103], v[102:103], v[174:175]
	v_pk_fma_f32 v[172:173], v[104:105], v[104:105], v[172:173]
	v_pk_fma_f32 v[174:175], v[106:107], v[106:107], v[174:175]
	v_pk_fma_f32 v[172:173], v[108:109], v[108:109], v[172:173]
	v_pk_fma_f32 v[174:175], v[110:111], v[110:111], v[174:175]
	v_pk_add_f32 v[172:173], v[172:173], v[174:175]
	s_sub_u32 s3, 0xffff, s20
	s_lshl_b32 s4, s3, 11
	v_add_f32_e32 v160, v172, v173
	s_add_u32 s16, s88, s4
	s_addc_u32 s17, s89, 0
	s_nop 1
	v_add_f32_dpp v160, v160, v160 quad_perm:[1,0,3,2] row_mask:0xf bank_mask:0xf bound_ctrl:1
	s_nop 1
	v_add_f32_dpp v160, v160, v160 quad_perm:[2,3,0,1] row_mask:0xf bank_mask:0xf bound_ctrl:1
	s_nop 1
	v_add_f32_dpp v160, v160, v160 row_half_mirror row_mask:0xf bank_mask:0xf bound_ctrl:1
	s_nop 1
	v_add_f32_dpp v160, v160, v160 row_mirror row_mask:0xf bank_mask:0xf bound_ctrl:1
	s_add_u32 s16, s16, 0x3c00000
	s_addc_u32 s17, s17, 0
	v_readlane_b32 s4, v160, 0
	v_readlane_b32 s5, v160, 16
	v_readlane_b32 s3, v160, 32
	s_nop 1
	v_mov_b32_e32 v161, s4
	v_add_f32_e32 v161, s5, v161
	v_readlane_b32 s4, v160, 48
	v_add_f32_e32 v161, s3, v161
	s_nop 1
	v_add_f32_e32 v160, s4, v161
	v_fmamk_f32 v160, v160, 0x3a800000, v170
	v_mul_f32_e32 v161, 0x4f800000, v160
	v_cmp_gt_f32_e32 vcc, v178, v160
	s_nop 1
	v_cndmask_b32_e32 v162, v160, v161, vcc
	v_sqrt_f32_e32 v164, v162
	s_nop 0
	v_add_u32_e32 v165, -1, v164
	v_add_u32_e32 v166, 1, v164
	v_fma_f32 v167, -v165, v164, v162
	v_fma_f32 v168, -v166, v164, v162
	v_cmp_ge_f32_e64 s[4:5], 0, v167
	s_nop 1
	v_cndmask_b32_e64 v164, v164, v165, s[4:5]
	v_cmp_lt_f32_e64 s[4:5], 0, v168
	s_nop 1
	v_cndmask_b32_e64 v164, v164, v166, s[4:5]
	v_mul_f32_e32 v165, 0x37800000, v164
	v_cndmask_b32_e32 v164, v164, v165, vcc
	v_cmp_class_f32_e32 vcc, v162, v171
	s_nop 1
	v_cndmask_b32_e32 v162, v164, v162, vcc
	v_div_scale_f32 v164, s[4:5], v162, v162, 1.0
	v_rcp_f32_e32 v165, v164
	v_div_scale_f32 v166, vcc, 1.0, v162, 1.0
	v_fma_f32 v167, -v164, v165, 1.0
	v_fmac_f32_e32 v165, v167, v165
	v_mul_f32_e32 v167, v166, v165
	v_fma_f32 v168, -v164, v167, v166
	v_fmac_f32_e32 v167, v168, v165
	v_fma_f32 v164, -v164, v167, v166
	v_div_fmas_f32 v164, v164, v165, v167
	v_div_fixup_f32 v162, v164, v162, 1.0
	v_pk_mul_f32 v[96:97], v[96:97], v[162:163] op_sel_hi:[1,0]
	v_pk_mul_f32 v[98:99], v[98:99], v[162:163] op_sel_hi:[1,0]
	v_pk_add_f32 v[112:113], v[112:113], 1.0 op_sel_hi:[1,0]
	v_pk_add_f32 v[114:115], v[114:115], 1.0 op_sel_hi:[1,0]
	v_pk_fma_f32 v[96:97], v[112:113], v[96:97], v[128:129]
	v_pk_fma_f32 v[98:99], v[114:115], v[98:99], v[130:131]
	v_cvt_pk_bf16_f32 v152, v96, v97
	v_cvt_pk_bf16_f32 v153, v98, v99
	v_pk_mul_f32 v[100:101], v[100:101], v[162:163] op_sel_hi:[1,0]
	v_pk_mul_f32 v[102:103], v[102:103], v[162:163] op_sel_hi:[1,0]
	v_pk_add_f32 v[116:117], v[116:117], 1.0 op_sel_hi:[1,0]
	v_pk_add_f32 v[118:119], v[118:119], 1.0 op_sel_hi:[1,0]
	v_pk_fma_f32 v[100:101], v[116:117], v[100:101], v[132:133]
	v_pk_fma_f32 v[102:103], v[118:119], v[102:103], v[134:135]
	v_cvt_pk_bf16_f32 v154, v100, v101
	v_cvt_pk_bf16_f32 v155, v102, v103
	v_pk_mul_f32 v[104:105], v[104:105], v[162:163] op_sel_hi:[1,0]
	v_pk_mul_f32 v[106:107], v[106:107], v[162:163] op_sel_hi:[1,0]
	v_pk_add_f32 v[120:121], v[120:121], 1.0 op_sel_hi:[1,0]
	v_pk_add_f32 v[122:123], v[122:123], 1.0 op_sel_hi:[1,0]
	v_pk_fma_f32 v[104:105], v[120:121], v[104:105], v[136:137]
	v_pk_fma_f32 v[106:107], v[122:123], v[106:107], v[138:139]
	v_cvt_pk_bf16_f32 v156, v104, v105
	v_cvt_pk_bf16_f32 v157, v106, v107
	v_pk_mul_f32 v[108:109], v[108:109], v[162:163] op_sel_hi:[1,0]
	v_pk_mul_f32 v[110:111], v[110:111], v[162:163] op_sel_hi:[1,0]
	v_pk_add_f32 v[124:125], v[124:125], 1.0 op_sel_hi:[1,0]
	v_pk_add_f32 v[126:127], v[126:127], 1.0 op_sel_hi:[1,0]
	v_pk_fma_f32 v[108:109], v[124:125], v[108:109], v[140:141]
	v_pk_fma_f32 v[110:111], v[126:127], v[110:111], v[142:143]
	v_cvt_pk_bf16_f32 v158, v108, v109
	v_cvt_pk_bf16_f32 v159, v110, v111
	global_store_dwordx2 v177, v[152:153], s[16:17]
	global_store_dwordx2 v177, v[154:155], s[16:17] offset:512
	global_store_dwordx2 v177, v[156:157], s[16:17] offset:1024
	global_store_dwordx2 v177, v[158:159], s[16:17] offset:1536
	s_add_i32 s20, s20, s1
	s_cmp_lt_u32 s20, 0x10000
	s_cselect_b32 s3, s20, s0
	s_sub_u32 s3, 0xffff, s3
	s_lshl_b32 s4, s3, 12
	s_add_u32 s6, s86, s4
	s_addc_u32 s7, s87, 0
	s_lshr_b32 s4, s3, 12
	s_mul_i32 s4, s4, 0x6000
	s_add_u32 s12, s88, s4
	s_addc_u32 s13, s89, 0
	s_add_u32 s14, s12, 0x164000
	s_addc_u32 s15, s13, 0
	s_add_u32 s12, s12, 0x163000
	s_addc_u32 s13, s13, 0
	global_load_dwordx4 v[96:99], v176, s[6:7]
	global_load_dwordx4 v[100:103], v176, s[6:7] offset:1024
	global_load_dwordx4 v[104:107], v176, s[6:7] offset:2048
	global_load_dwordx4 v[108:111], v176, s[6:7] offset:3072
	global_load_dwordx4 v[112:115], v176, s[14:15]
	global_load_dwordx4 v[116:119], v176, s[14:15] offset:1024
	global_load_dwordx4 v[120:123], v176, s[14:15] offset:2048
	global_load_dwordx4 v[124:127], v176, s[14:15] offset:3072
	global_load_dwordx4 v[128:131], v176, s[12:13]
	global_load_dwordx4 v[132:135], v176, s[12:13] offset:1024
	global_load_dwordx4 v[136:139], v176, s[12:13] offset:2048
	global_load_dwordx4 v[140:143], v176, s[12:13] offset:3072
	s_branch .LNb_loop
